# move w_ffn_out bf16 conversion from E tail to A tail (A tail has slack; E(0) tail was critical)
# speedup vs baseline: 1.0036x; 1.0036x over previous
.LBB0_198:
	s_add_u32 s2, s86, 0x400000
	v_writelane_b32 v251, s2, 30
	s_addc_u32 s2, s87, 0
	v_writelane_b32 v251, s2, 31
	s_add_u32 s2, s86, 0xc00000
	v_writelane_b32 v251, s2, 32
	s_addc_u32 s2, s87, 0
	s_add_u32 s36, s86, 0x6e00000
	s_addc_u32 s37, s87, 0
	v_writelane_b32 v251, s2, 33
	s_add_u32 s2, s86, 0x100000
	v_writelane_b32 v251, s2, 34
	s_addc_u32 s2, s87, 0
	v_writelane_b32 v251, s2, 35
	s_add_u32 s2, s86, 0x4c00000
	s_addc_u32 s3, s87, 0
	s_add_u32 s6, s86, 0x300000
	v_writelane_b32 v250, s2, 51
	s_addc_u32 s7, s87, 0
	s_load_dwordx16 s[40:55], s[0:1], 0x58
	v_writelane_b32 v250, s3, 52
	s_add_u32 s2, s86, 0x500000
	v_writelane_b32 v251, s2, 36
	s_addc_u32 s2, s87, 0
	s_cmpk_eq_i32 s33, 0x100
	v_writelane_b32 v251, s2, 37
	s_cselect_b64 s[2:3], -1, 0
	v_writelane_b32 v250, s2, 55
	s_lshl_b32 s64, s76, 14
	s_add_i32 s11, s64, 0
	v_writelane_b32 v250, s3, 56
	v_mov_b32_e32 v15, 0
	v_readlane_b32 s27, v250, 2
	s_lshl_b32 s2, s27, 3
	s_add_i32 s4, s76, s2
	s_add_i32 s2, s4, 0x3e0
	v_writelane_b32 v251, s2, 38
	s_add_u32 s2, s86, 0x900000
	s_addc_u32 s3, s87, 0
	v_writelane_b32 v251, s2, 24
	v_mov_b32_e32 v229, 0x358637bd
	v_mov_b32_e32 v231, 0xc0135761
	v_writelane_b32 v251, s3, 25
	s_lshl_b32 s2, s33, 2
	v_writelane_b32 v251, s2, 39
	s_add_u32 s2, s84, 0x4a16000
	v_writelane_b32 v251, s2, 40
	s_addc_u32 s2, s85, 0
	v_writelane_b32 v251, s2, 41
	s_add_u32 s2, s84, 0x4200000
	v_writelane_b32 v251, s2, 42
	s_addc_u32 s2, s85, 0
	s_add_u32 s74, s86, 0xc080000
	s_addc_u32 s75, s87, 0
	v_writelane_b32 v251, s2, 43
	s_add_u32 s2, s86, 0xe180000
	s_addc_u32 s3, s87, 0
	s_add_u32 s12, s86, 0x9f80000
	v_writelane_b32 v250, s2, 53
	s_addc_u32 s13, s87, 0
	v_bfrev_b32_e32 v244, 0.5
	v_writelane_b32 v250, s3, 54
	s_add_u32 s2, s86, 0x1200
	s_addc_u32 s3, s87, 0
	v_writelane_b32 v251, s2, 44
	v_readlane_b32 s8, v250, 4
	v_readlane_b32 s9, v250, 5
	v_writelane_b32 v251, s3, 45
	s_add_u32 s2, s8, 0x400
	s_addc_u32 s3, s9, 0
	v_writelane_b32 v251, s2, 46
	v_readlane_b32 s5, v250, 6
	v_readlane_b32 s25, v250, 3
	v_writelane_b32 v251, s3, 47
	s_add_u32 s2, s8, 0x500
	s_addc_u32 s3, s9, 0
	v_writelane_b32 v251, s2, 48
	v_mov_b32_e32 v236, 0x422c0000
	v_mov_b32_e32 v246, 0xff800000
	v_writelane_b32 v251, s3, 49
	s_add_u32 s2, s8, 0x600
	s_addc_u32 s3, s9, 0
	v_writelane_b32 v251, s2, 50
	v_mov_b32_e32 v247, 0x2c00
	s_movk_i32 s72, 0x80
	v_writelane_b32 v251, s3, 51
	s_add_u32 s2, s8, 0x700
	s_addc_u32 s3, s9, 0
	v_writelane_b32 v251, s2, 52
	s_mov_b32 s66, 0x8000
	s_mov_b32 s67, 0x10000
	v_writelane_b32 v251, s3, 53
	s_add_u32 s2, s8, 0x800
	s_addc_u32 s3, s9, 0
	v_writelane_b32 v251, s2, 54
	s_mov_b32 s68, 0x18000
	s_mov_b32 s69, 0xffff0000
	v_writelane_b32 v251, s3, 55
	s_add_u32 s2, s8, 0x900
	s_addc_u32 s3, s9, 0
	v_writelane_b32 v251, s2, 56
	s_mov_b32 s31, 0x41000000
	s_mov_b64 s[94:95], 0x60000
	v_writelane_b32 v251, s3, 57
	s_add_u32 s2, s8, 0xa00
	s_addc_u32 s3, s9, 0
	v_writelane_b32 v251, s2, 58
	s_mov_b64 s[96:97], 0x80000
	s_nop 0
	v_writelane_b32 v251, s3, 59
	s_add_u32 s2, s8, 0xb00
	s_addc_u32 s3, s9, 0
	v_writelane_b32 v251, s2, 60
	s_nop 1
	v_writelane_b32 v251, s3, 61
	s_add_u32 s2, s8, 0xc00
	s_addc_u32 s3, s9, 0
	v_writelane_b32 v251, s2, 62
	s_nop 1
	v_writelane_b32 v251, s3, 63
	s_add_u32 s2, s8, 0xd00
	s_addc_u32 s3, s9, 0
	v_writelane_b32 v252, s2, 0
	s_nop 1
	v_writelane_b32 v252, s3, 1
	s_add_u32 s2, s8, 0xe00
	s_addc_u32 s3, s9, 0
	v_writelane_b32 v252, s2, 2
	s_nop 1
	v_writelane_b32 v252, s3, 3
	s_add_u32 s2, s8, 0xf00
	s_addc_u32 s3, s9, 0
	v_writelane_b32 v252, s2, 4
	s_nop 1
	v_writelane_b32 v252, s3, 5
	s_add_u32 s2, s8, 0x1000
	s_addc_u32 s3, s9, 0
	v_writelane_b32 v252, s2, 6
	s_nop 1
	v_writelane_b32 v252, s3, 7
	s_add_u32 s2, s8, 0x1100
	s_addc_u32 s3, s9, 0
	v_writelane_b32 v252, s2, 8
	s_nop 1
	v_writelane_b32 v252, s3, 9
	s_add_u32 s2, s8, 0x1200
	s_addc_u32 s3, s9, 0
	v_writelane_b32 v252, s2, 10
	s_nop 1
	v_writelane_b32 v252, s3, 11
	s_add_u32 s2, s8, 0x1300
	s_addc_u32 s3, s9, 0
	v_writelane_b32 v252, s2, 12
	s_cmp_eq_u32 s5, 15
	s_nop 0
	v_writelane_b32 v252, s3, 13
	s_cselect_b64 s[2:3], -1, 0
	v_writelane_b32 v252, s2, 14
	s_cmp_eq_u32 s5, 14
	s_nop 0
	v_writelane_b32 v252, s3, 15
	s_cselect_b64 s[2:3], -1, 0
	v_writelane_b32 v252, s2, 16
	s_cmp_eq_u32 s5, 13
	s_nop 0
	v_writelane_b32 v252, s3, 17
	s_cselect_b64 s[2:3], -1, 0
	v_writelane_b32 v252, s2, 18
	s_cmp_eq_u32 s5, 12
	s_nop 0
	v_writelane_b32 v252, s3, 19
	s_cselect_b64 s[2:3], -1, 0
	v_writelane_b32 v252, s2, 20
	s_cmp_eq_u32 s5, 11
	s_nop 0
	v_writelane_b32 v252, s3, 21
	s_cselect_b64 s[2:3], -1, 0
	v_writelane_b32 v252, s2, 22
	s_cmp_eq_u32 s5, 10
	s_nop 0
	v_writelane_b32 v252, s3, 23
	s_cselect_b64 s[2:3], -1, 0
	v_writelane_b32 v252, s2, 24
	s_cmp_eq_u32 s5, 9
	s_nop 0
	v_writelane_b32 v252, s3, 25
	s_cselect_b64 s[2:3], -1, 0
	v_writelane_b32 v252, s2, 26
	s_cmp_eq_u32 s5, 8
	s_nop 0
	v_writelane_b32 v252, s3, 27
	s_cselect_b64 s[2:3], -1, 0
	v_writelane_b32 v252, s2, 28
	s_cmp_eq_u32 s5, 7
	s_nop 0
	v_writelane_b32 v252, s3, 29
	s_cselect_b64 s[2:3], -1, 0
	v_writelane_b32 v252, s2, 30
	s_cmp_eq_u32 s5, 6
	s_nop 0
	v_writelane_b32 v252, s3, 31
	s_cselect_b64 s[2:3], -1, 0
	v_writelane_b32 v252, s2, 32
	s_cmp_eq_u32 s5, 5
	s_nop 0
	v_writelane_b32 v252, s3, 33
	s_cselect_b64 s[2:3], -1, 0
	v_writelane_b32 v252, s2, 34
	s_cmp_eq_u32 s5, 4
	s_nop 0
	v_writelane_b32 v252, s3, 35
	s_cselect_b64 s[2:3], -1, 0
	v_writelane_b32 v252, s2, 36
	s_cmp_eq_u32 s5, 3
	s_nop 0
	v_writelane_b32 v252, s3, 37
	s_cselect_b64 s[2:3], -1, 0
	v_writelane_b32 v252, s2, 38
	s_cmp_eq_u32 s5, 2
	s_nop 0
	v_writelane_b32 v252, s3, 39
	s_cselect_b64 s[2:3], -1, 0
	v_writelane_b32 v252, s2, 40
	s_cmp_eq_u32 s5, 1
	s_nop 0
	v_writelane_b32 v252, s3, 41
	s_cselect_b64 s[2:3], -1, 0
	v_writelane_b32 v252, s2, 42
	s_cmp_eq_u32 s5, 0
	s_nop 0
	v_writelane_b32 v252, s3, 43
	s_cselect_b64 s[2:3], -1, 0
	v_writelane_b32 v252, s2, 44
	s_nop 1
	v_writelane_b32 v252, s3, 45
	s_lshl_b32 s2, 1, s5
	v_writelane_b32 v252, s2, 46
	s_lshl_b32 s2, s5, 8
	s_add_u32 s2, s8, s2
	s_addc_u32 s3, s9, 0
	s_add_u32 s2, s2, 0x1400
	s_addc_u32 s3, s3, 0
	v_writelane_b32 v252, s2, 47
	s_nop 1
	v_writelane_b32 v252, s3, 48
	s_lshl_b32 s2, s5, 2
	s_add_u32 s2, s8, s2
	s_addc_u32 s3, s9, 0
	s_add_u32 s2, s2, 0x3700
	s_addc_u32 s3, s3, 0
	v_writelane_b32 v252, s2, 49
	s_and_b32 s5, s25, 1
	s_nop 0
	v_writelane_b32 v252, s3, 50
	s_bfe_u32 s2, s25, 0x40001
	s_mul_i32 s3, s2, 0x56
	s_lshr_b32 s3, s3, 8
	s_mul_i32 s3, s3, 3
	s_sub_i32 s2, s2, s3
	s_lshr_b32 s3, s25, 4
	s_and_b32 s3, s3, 6
	s_or_b32 s15, s3, s5
	s_and_b32 s10, s2, 0xff
	s_cmpk_lg_i32 s33, 0x100
	s_cselect_b64 s[2:3], -1, 0
	s_and_b64 s[8:9], s[2:3], exec
	s_cselect_b32 s8, 2, s10
	s_cmpk_lt_i32 s25, 0x200
	s_cselect_b64 s[16:17], -1, 0
	v_writelane_b32 v251, s16, 9
	s_and_b64 s[2:3], s[2:3], s[16:17]
	s_add_u32 s81, s86, 0x7e80000
	v_writelane_b32 v252, s2, 51
	s_addc_u32 s82, s87, 0
	s_add_u32 s30, s86, 0x8f00000
	v_writelane_b32 v252, s3, 52
	s_mul_i32 s2, s76, 0xffffc400
	v_writelane_b32 v251, s17, 10
	s_addc_u32 s83, s87, 0
	s_add_i32 s16, s11, s2
	s_lshl_b32 s2, s76, 8
	s_add_i32 s2, s2, 0
	s_lshl_b32 s93, s76, 3
	s_lshl_b32 s9, s76, 4
	s_add_i32 s78, s2, 0x10400
	s_lshr_b32 s92, s73, 7
	s_lshl_b32 s19, s76, 5
	s_and_b32 s2, s9, 48
	s_and_b32 s20, s93, 0x1fffffe0
	s_add_u32 s21, s86, 0x10280000
	s_addc_u32 s24, s87, 0
	s_cmp_eq_u32 s8, 0
	v_writelane_b32 v252, s11, 53
	v_writelane_b32 v250, s2, 31
	s_cselect_b64 s[2:3], -1, 0
	v_writelane_b32 v252, s2, 54
	s_cmpk_lt_i32 s25, 0x100
	v_writelane_b32 v250, s20, 33
	v_writelane_b32 v252, s3, 55
	s_cselect_b64 s[2:3], -1, 0
	v_writelane_b32 v251, s2, 11
	s_cmp_lt_u32 s73, 64
	s_cselect_b64 s[22:23], -1, 0
	v_writelane_b32 v251, s3, 12
	s_and_b32 s2, s33, 3
	s_cmp_eq_u32 s2, 0
	s_cselect_b64 s[2:3], -1, 0
	v_writelane_b32 v252, s2, 56
	v_writelane_b32 v250, s21, 39
	v_writelane_b32 v250, s24, 41
	v_writelane_b32 v252, s3, 57
	s_lshl_b32 s2, s25, 16
	s_and_b32 s2, s2, 0x30000
	s_waitcnt lgkmcnt(0)
	s_add_u32 s2, s50, s2
	v_writelane_b32 v252, s2, 58
	s_addc_u32 s2, s51, 0
	v_writelane_b32 v252, s2, 59
	s_add_u32 s2, s86, 0xb000000
	v_writelane_b32 v252, s2, 60
	s_addc_u32 s2, s87, 0
	v_writelane_b32 v252, s2, 61
	s_bfe_u32 s2, s73, 0x10006
	s_and_b32 s26, s9, 0x3fffffe0
	s_cmpk_lt_u32 s73, 0x200
	s_mul_i32 s3, s76, 0x2200
	v_writelane_b32 v252, s26, 62
	s_cselect_b64 s[10:11], -1, 0
	s_add_i32 s3, s3, 0
	v_writelane_b32 v252, s10, 63
	s_add_i32 s3, s3, 0x10800
	s_nop 0
	v_writelane_b32 v253, s11, 0
	v_writelane_b32 v253, s3, 1
	s_lshl_b32 s3, s2, 14
	s_or_b32 s10, s76, 1
	v_writelane_b32 v253, s3, 2
	s_lshl_b32 s3, s2, 6
	s_lshl_b32 s11, s2, 7
	v_writelane_b32 v253, s3, 3
	s_add_u32 s2, s12, s11
	v_writelane_b32 v253, s2, 4
	s_addc_u32 s2, s13, 0
	s_cmpk_lt_i32 s25, 0x80
	v_writelane_b32 v253, s2, 5
	s_cselect_b64 s[2:3], -1, 0
	v_writelane_b32 v251, s2, 13
	s_nop 1
	v_writelane_b32 v251, s3, 14
	s_add_u32 s2, s84, 0x4e16000
	v_writelane_b32 v253, s2, 6
	s_addc_u32 s2, s85, 0
	s_cmpk_lt_u32 s73, 0x80
	v_writelane_b32 v253, s2, 7
	s_cselect_b64 s[2:3], -1, 0
	v_writelane_b32 v253, s2, 8
	v_writelane_b32 v251, s12, 5
	v_writelane_b32 v251, s13, 7
	v_writelane_b32 v253, s3, 9
	s_and_b32 s2, s73, 64
	v_writelane_b32 v253, s2, 10
	s_lshl_b32 s2, s2, 1
	s_add_u32 s2, s12, s2
	v_writelane_b32 v253, s2, 11
	s_addc_u32 s2, s13, 0
	v_writelane_b32 v253, s2, 12
	s_lshl_b32 s2, s25, 1
	s_and_b32 s12, s2, 60
	s_ashr_i32 s2, s25, 7
	s_ashr_i32 s3, s2, 31
	s_xor_b32 s13, s12, 0x7c
	s_lshl_b32 s13, s13, 6
	s_lshl_b64 s[28:29], s[2:3], 13
	s_or_b32 s14, s13, s28
	s_add_u32 s34, s14, s19
	s_addc_u32 s35, s29, 0
	v_writelane_b32 v253, s34, 13
	s_nop 1
	v_writelane_b32 v253, s35, 14
	v_writelane_b32 v253, s15, 15
	s_lshl_b32 s15, s15, 7
	s_add_u32 s34, s36, s15
	s_addc_u32 s35, s37, 0
	v_writelane_b32 v253, s34, 16
	v_writelane_b32 v255, s36, 0
	s_nop 0
	v_writelane_b32 v253, s35, 17
	s_add_u32 s34, s81, s15
	s_addc_u32 s35, s82, 0
	v_writelane_b32 v253, s34, 18
	s_add_u32 s17, s30, s15
	s_addc_u32 s18, s83, 0
	v_writelane_b32 v253, s35, 19
	s_add_i32 s34, s13, 0xfffffe00
	s_lshl_b32 s13, s20, 1
	s_or_b32 s20, s28, s34
	s_add_u32 s38, s17, s13
	s_addc_u32 s39, s18, 0
	v_writelane_b32 v253, s38, 20
	s_add_i32 s18, s14, 0xfffffe40
	v_writelane_b32 v255, s37, 1
	v_writelane_b32 v253, s39, 21
	s_add_i32 s38, s14, 0xfffffe80
	s_add_u32 s14, s21, s15
	s_addc_u32 s15, s24, 0
	v_writelane_b32 v253, s14, 22
	s_cmp_eq_u32 s8, 1
	s_mov_b32 s21, s29
	v_writelane_b32 v253, s15, 23
	s_cselect_b64 s[14:15], -1, 0
	s_xor_b32 s12, s12, 60
	v_writelane_b32 v253, s14, 24
	s_lshl_b32 s13, s12, 6
	v_sub_u32_e64 v1, s12, 8 clamp
	v_writelane_b32 v253, s15, 25
	s_or_b32 s14, s28, s13
	s_add_u32 s14, s14, s19
	v_writelane_b32 v253, s19, 26
	s_addc_u32 s15, s29, 0
	v_writelane_b32 v253, s14, 27
	s_mov_b32 s19, s29
	s_mov_b32 s39, s29
	v_writelane_b32 v253, s15, 28
	v_readfirstlane_b32 s14, v1
	s_lshl_b32 s15, s14, 6
	s_or_b32 s28, s15, s28
	s_sub_i32 s14, s12, s14
	s_add_i32 s14, s14, 4
	s_or_b32 s24, s28, 64
	s_or_b32 s50, s28, 0x80
	s_cmp_gt_i32 s14, 0
	v_writelane_b32 v253, s14, 29
	s_cselect_b64 s[14:15], -1, 0
	v_writelane_b32 v253, s14, 30
	s_cmp_eq_u32 s8, 2
	v_writelane_b32 v255, s74, 2
	v_writelane_b32 v253, s15, 31
	s_cselect_b64 s[14:15], -1, 0
	v_writelane_b32 v253, s14, 32
	v_writelane_b32 v255, s75, 3
	s_nop 0
	v_writelane_b32 v253, s15, 33
	s_add_u32 s14, s86, 0x12380000
	s_addc_u32 s15, s87, 0
	v_writelane_b32 v251, s14, 3
	s_add_u32 s8, s86, 0x12280000
	v_writelane_b32 v250, s8, 12
	v_writelane_b32 v251, s15, 4
	s_addc_u32 s8, s87, 0
	v_writelane_b32 v251, s8, 21
	s_add_u32 s8, s86, 0xa80000
	v_writelane_b32 v253, s8, 34
	s_addc_u32 s8, s87, 0
	v_writelane_b32 v253, s8, 35
	s_add_u32 s8, s86, 0x14380000
	v_writelane_b32 v253, s8, 36
	s_addc_u32 s8, s87, 0
	s_add_u32 s14, s86, 0x14600000
	v_writelane_b32 v253, s8, 37
	s_addc_u32 s15, s87, 0
	v_writelane_b32 v253, s14, 38
	s_add_u32 s8, s86, 0x700000
	s_nop 0
	v_writelane_b32 v253, s15, 39
	v_writelane_b32 v253, s8, 40
	s_addc_u32 s8, s87, 0
	v_writelane_b32 v253, s8, 41
	s_add_i32 s8, s4, 0x1820
	s_cmpk_gt_i32 s27, 0xd0
	v_writelane_b32 v253, s8, 42
	s_cselect_b64 s[14:15], -1, 0
	v_writelane_b32 v253, s14, 43
	s_nop 1
	v_writelane_b32 v253, s15, 44
	s_add_u32 s14, s86, 0x1cf000
	s_addc_u32 s15, s87, 0
	v_writelane_b32 v253, s14, 45
	s_nop 1
	v_writelane_b32 v253, s15, 46
	s_add_i32 s14, s4, 0xfffff978
	s_cmpk_lt_i32 s14, 0x160
	s_cselect_b64 s[56:57], -1, 0
	v_writelane_b32 v253, s56, 47
	s_nop 1
	v_writelane_b32 v253, s57, 48
	s_add_u32 s56, s86, 0x7bb000
	s_addc_u32 s57, s87, 0
	v_writelane_b32 v253, s56, 49
	s_nop 1
	v_writelane_b32 v253, s57, 50
	s_add_u32 s56, s86, 0x1cc000
	s_addc_u32 s57, s87, 0
	v_writelane_b32 v253, s56, 51
	s_addk_i32 s4, 0xfaa0
	s_cmpk_lt_i32 s4, 0x120
	v_writelane_b32 v253, s57, 52
	v_writelane_b32 v253, s4, 53
	s_cselect_b64 s[56:57], -1, 0
	v_writelane_b32 v253, s56, 54
	s_nop 1
	v_writelane_b32 v253, s57, 55
	s_add_u32 s56, s86, 0x599000
	s_addc_u32 s57, s87, 0
	v_writelane_b32 v253, s56, 56
	s_nop 1
	v_writelane_b32 v253, s57, 57
	s_add_u32 s56, s86, 0x1476b000
	s_addc_u32 s57, s87, 0
	s_add_u32 s70, s84, 0x5016000
	v_writelane_b32 v253, s56, 58
	s_addc_u32 s71, s85, 0
	s_add_u32 s4, s86, 0xc600000
	v_writelane_b32 v253, s57, 59
	v_writelane_b32 v253, s4, 60
	s_addc_u32 s4, s87, 0
	s_cmp_eq_u64 s[84:85], 0
	v_writelane_b32 v253, s4, 61
	s_cselect_b64 s[56:57], -1, 0
	s_or_b32 s4, s9, 16
	v_writelane_b32 v254, s4, 0
	s_or_b32 s4, s9, 24
	v_writelane_b32 v254, s4, 1
	s_add_i32 s4, s11, 0
	s_add_i32 s4, s4, 0x10010
	v_writelane_b32 v254, s4, 2
	s_add_i32 s4, s10, 1
	v_writelane_b32 v254, s4, 3
	s_lshl_b32 s4, s92, 8
	s_add_i32 s4, s4, 0
	s_add_i32 s4, s4, s11
	s_add_i32 s4, s4, 0x10810
	v_writelane_b32 v254, s4, 4
	s_or_b32 s8, s26, 8
	v_writelane_b32 v254, s8, 5
	s_lshl_b32 s8, s25, 7
	s_lshr_b32 s4, s73, 2
	v_writelane_b32 v251, s8, 15
	s_lshl_b32 s8, s33, 7
	s_lshl_b64 s[2:3], s[2:3], 23
	s_and_b32 s4, s4, 0x3fffffc0
	v_writelane_b32 v254, s8, 6
	s_add_i32 s8, s92, 8
	s_add_u32 s4, s2, s4
	v_writelane_b32 v254, s8, 7
	s_addc_u32 s8, s3, 0
	s_lshl_b32 s9, s25, 3
	s_lshl_b32 s5, s5, 7
	s_and_b32 s9, s9, 0x300
	s_or_b32 s5, s9, s5
	s_add_u32 s4, s4, s5
	s_addc_u32 s8, s8, 0
	s_add_u32 s4, s86, s4
	s_addc_u32 s8, s87, s8
	s_add_u32 s26, s4, 0x8f30000
	s_addc_u32 s27, s8, 0
	s_or_b32 s2, s2, s5
	s_add_u32 s2, s86, s2
	s_addc_u32 s3, s87, s3
	v_writelane_b32 v254, s26, 8
	s_add_u32 s2, s2, 0x7eb0000
	s_addc_u32 s3, s3, 0
	v_writelane_b32 v254, s27, 9
	v_writelane_b32 v254, s2, 10
	s_mov_b32 s25, s29
	v_writelane_b32 v253, s56, 62
	v_writelane_b32 v254, s3, 11
	v_writelane_b32 v254, s20, 12
	s_min_u32 s2, s12, 8
	s_add_i32 s3, s2, s92
	v_writelane_b32 v254, s21, 13
	v_writelane_b32 v254, s18, 14
	s_lshl_b32 s3, s3, 8
	s_add_i32 s3, s3, 0
	v_writelane_b32 v254, s19, 15
	v_writelane_b32 v254, s38, 16
	s_mov_b32 s19, 0
	s_mov_b32 s35, s19
	v_writelane_b32 v254, s39, 17
	v_writelane_b32 v254, s24, 18
	s_add_i32 s3, s3, s11
	s_add_i32 s3, s3, 0x10010
	v_writelane_b32 v254, s25, 19
	v_writelane_b32 v254, s28, 20
	s_mov_b32 s51, s29
	v_writelane_b32 v253, s57, 63
	v_writelane_b32 v254, s29, 21
	v_writelane_b32 v254, s50, 22
	s_load_dwordx8 s[56:63], s[0:1], 0x98
	v_writelane_b32 v251, s92, 1
	v_writelane_b32 v254, s51, 23
	v_writelane_b32 v254, s34, 24
	v_writelane_b32 v251, s70, 28
	s_movk_i32 s73, 0x1600
	v_writelane_b32 v254, s35, 25
	v_writelane_b32 v254, s3, 26
	s_lshl_b32 s3, s2, 6
	s_sub_i32 s4, s13, s3
	s_ashr_i32 s5, s4, 31
	v_writelane_b32 v254, s4, 27
	s_lshl_b32 s2, s2, 13
	s_add_i32 s3, s2, 0x8000
	v_writelane_b32 v254, s5, 28
	v_writelane_b32 v254, s3, 29
	s_bitset1_b32 s2, 14
	v_writelane_b32 v254, s2, 30
	s_waitcnt lgkmcnt(0)
	s_add_u32 s2, s60, 0x1af6800
	v_writelane_b32 v254, s56, 31
	s_addc_u32 s3, s61, 0
	s_mov_b64 s[34:35], 0x80
	v_writelane_b32 v254, s57, 32
	v_writelane_b32 v254, s58, 33
	v_writelane_b32 v254, s59, 34
	v_writelane_b32 v254, s60, 35
	v_writelane_b32 v254, s61, 36
	v_writelane_b32 v254, s62, 37
	v_writelane_b32 v254, s63, 38
	s_mov_b64 s[58:59], s[54:55]
	s_mov_b64 s[56:57], s[52:53]
	s_mov_b64 s[52:53], s[48:49]
	s_mov_b64 s[50:51], s[46:47]
	s_mov_b64 s[48:49], s[44:45]
	s_mov_b64 s[46:47], s[42:43]
	s_mov_b64 s[44:45], s[40:41]
	v_writelane_b32 v250, s44, 15
	v_writelane_b32 v254, s2, 39
	s_movk_i32 s60, 0x2c00
	v_writelane_b32 v250, s45, 16
	v_writelane_b32 v250, s46, 17
	v_writelane_b32 v254, s3, 40
	s_lshl_b32 s2, s14, 3
	v_writelane_b32 v250, s47, 18
	v_writelane_b32 v254, s2, 41
	v_writelane_b32 v250, s48, 19
	v_writelane_b32 v254, s14, 42
	s_lshl_b32 s2, s14, 4
	v_writelane_b32 v250, s49, 20
	v_writelane_b32 v254, s2, 43
	s_add_u32 s2, s40, 0x160f800
	v_writelane_b32 v250, s50, 21
	v_writelane_b32 v250, s51, 22
	s_addc_u32 s3, s41, 0
	v_writelane_b32 v250, s52, 23
	v_writelane_b32 v254, s2, 44
	v_writelane_b32 v250, s53, 24
	v_writelane_b32 v250, s54, 25
	v_writelane_b32 v254, s3, 45
	s_mul_i32 s2, s92, 0x1100
	v_writelane_b32 v254, s2, 46
	s_add_i32 s2, 0, 0x21000
	v_writelane_b32 v250, s55, 26
	v_writelane_b32 v254, s2, 47
	s_add_i32 s2, 0, 0x22800
	v_writelane_b32 v250, s56, 27
	v_writelane_b32 v254, s2, 48
	s_add_i32 s2, 0, 0x27160
	v_writelane_b32 v250, s57, 28
	v_writelane_b32 v254, s2, 49
	s_add_i32 s2, 0, 0x27164
	v_writelane_b32 v250, s58, 29
	v_writelane_b32 v254, s2, 50
	s_add_i32 s2, 0, 0x27168
	v_writelane_b32 v250, s59, 30
	v_writelane_b32 v254, s2, 51
	s_add_i32 s2, 0, 0x10210
	v_writelane_b32 v250, s2, 35
	s_add_i32 s2, 0, 0x10110
	v_writelane_b32 v250, s2, 37
	s_load_dwordx2 s[2:3], s[0:1], 0x20
	s_load_dwordx4 s[88:91], s[0:1], 0x10
	s_load_dwordx4 s[8:11], s[0:1], 0xb8
	v_cmp_gt_u32_e64 s[0:1], 16, v0
	v_writelane_b32 v250, s64, 43
	v_writelane_b32 v250, s81, 14
	s_waitcnt lgkmcnt(0)
	v_writelane_b32 v254, s2, 52
	v_writelane_b32 v250, s82, 13
	v_writelane_b32 v250, s30, 59
	v_writelane_b32 v254, s3, 53
	v_writelane_b32 v254, s8, 54
	v_writelane_b32 v250, s83, 61
	v_writelane_b32 v250, s78, 63
	v_writelane_b32 v254, s9, 55
	v_writelane_b32 v254, s10, 56
	v_writelane_b32 v254, s11, 57
	v_writelane_b32 v254, s0, 58
	s_mov_b32 s8, s19
	v_writelane_b32 v250, s93, 57
	v_writelane_b32 v254, s1, 59
	s_mov_b64 s[0:1], -1
	v_writelane_b32 v254, s0, 60
	v_writelane_b32 v251, s71, 29
	s_nop 0
	v_writelane_b32 v254, s1, 61
	v_writelane_b32 v254, s0, 62
	s_nop 1
	v_writelane_b32 v254, s1, 63
	s_branch .LBB0_203

.LBB0_203:
	s_mul_i32 s0, s8, 6
	v_writelane_b32 v255, s0, 4
	s_add_i32 s2, s0, 2
	s_mul_i32 s0, s8, 0x1d80000
	v_readlane_b32 s1, v251, 32
	s_add_u32 s0, s1, s0
	v_writelane_b32 v251, s0, 26
	s_mov_b32 s9, s19
	v_readlane_b32 s0, v251, 33
	s_addc_u32 s0, s0, 0
	s_nop 0
	v_writelane_b32 v250, s0, 6
	s_nop 0
	v_readlane_b32 s4, v250, 8
	v_readlane_b32 s5, v250, 9
	s_cmp_le_i32 s4, s2
	s_cselect_b64 s[0:1], -1, 0
	s_cmp_lt_i32 s2, s5
	s_cselect_b64 s[2:3], -1, 0
	s_and_b64 s[0:1], s[0:1], s[2:3]
	v_writelane_b32 v255, s0, 5
	s_andn2_b64 vcc, exec, s[0:1]
	s_nop 0
	v_writelane_b32 v255, s1, 6
	v_writelane_b32 v255, s8, 7
	s_nop 1
	v_writelane_b32 v255, s9, 8
	s_cbranch_vccnz .LBB0_608
	s_mov_b32 s20, 1
	s_mov_b32 s100, 0
	s_cmp_lt_i32 s20, 1
	s_cbranch_scc1 .LBB0_608
	v_readlane_b32 s4, v255, 7
	s_lshl_b32 s18, s4, 6
	s_mul_i32 s0, s4, 0x99000
	v_readlane_b32 s1, v251, 36
	s_add_u32 s79, s1, s0
	v_readlane_b32 s0, v251, 37
	s_addc_u32 s80, s0, 0
	s_mul_i32 s0, s4, 0x1d80
	v_readlane_b32 s1, v251, 38
	s_add_i32 s2, s0, 0x1d80
	s_add_i32 s0, s1, s0
	s_cmp_lt_i32 s0, s2
	v_readlane_b32 s5, v255, 8
	v_writelane_b32 v255, s0, 9
	s_cselect_b64 s[0:1], -1, 0
	v_writelane_b32 v251, s2, 19
	v_writelane_b32 v255, s0, 10
	v_readlane_b32 s2, v251, 40
	s_mov_b32 s21, 0
	v_writelane_b32 v255, s1, 11
	s_lshl_b64 s[0:1], s[4:5], 20
	s_add_u32 s0, s2, s0
	v_writelane_b32 v255, s0, 12
	v_readlane_b32 s0, v251, 41
	s_addc_u32 s0, s0, s1
	s_nop 0
	v_writelane_b32 v255, s0, 14
	s_lshl_b32 s0, s4, 1
	v_writelane_b32 v255, s0, 16
	s_lshl_b64 s[0:1], s[18:19], 2
	v_writelane_b32 v251, s0, 22
	v_writelane_b32 v255, s20, 17
	s_nop 0
	v_writelane_b32 v251, s1, 23
	s_branch .LBB0_208
